# GLA scan: prefetch-issued path gets counted vmcnt(23..18) in unrolled steps 2-4 (was draining prefetch)
# speedup vs baseline: 1.0048x; 1.0048x over previous
.LBB0_480:
	s_or_b64 exec, exec, s[52:53]
	s_add_i32 s10, s85, 0xffffff40
	s_add_i32 s87, s86, 0xc0
	s_and_b64 s[52:53], s[48:49], exec
	s_cselect_b32 s10, s10, s87
	v_lshl_add_u64 v[16:17], v[148:149], 0, s[10:11]
	v_lshlrev_b64 v[16:17], 11, v[16:17]
	v_lshl_add_u64 v[16:17], v[146:147], 0, v[16:17]
	global_load_dwordx4 v[96:99], v[16:17], off
	s_waitcnt vmcnt(23)
	ds_write_b128 v202, v[68:71] offset:17408
	s_waitcnt vmcnt(22)
	ds_write_b128 v202, v[72:75] offset:17424
	s_waitcnt vmcnt(21)
	ds_write_b128 v203, v[76:79] offset:34816
	s_waitcnt vmcnt(20)
	ds_write_b128 v203, v[80:83] offset:34832
	s_waitcnt vmcnt(19)
	ds_write_b128 v204, v[84:87] offset:53248
	s_waitcnt vmcnt(18)
	s_branch .Lsw0_join

.Lsw0_join:
	ds_write_b16 v144, v120 offset:62464
	ds_write_b16_d16_hi v144, v120 offset:62608
	ds_write_b16 v144, v121 offset:62752
	ds_write_b16_d16_hi v144, v121 offset:62896
	ds_write_b16 v144, v122 offset:63040
	ds_write_b16_d16_hi v144, v122 offset:63184
	ds_write_b16 v144, v123 offset:63328
	ds_write_b16_d16_hi v144, v123 offset:63472
	s_and_saveexec_b64 s[52:53], s[0:1]
	ds_write_b32 v205, v198
	s_or_b64 exec, exec, s[52:53]
	s_waitcnt lgkmcnt(0)
	s_barrier
	s_and_saveexec_b64 s[52:53], s[4:5]
	s_cbranch_execz .LBB0_485
	ds_read_b128 v[16:19], v209 offset:53248
	ds_read_b128 v[20:23], v210 offset:62464
	ds_read_b128 v[32:35], v209 offset:53280
	ds_read_b128 v[36:39], v210 offset:62496
	s_add_i32 s10, s85, 0xfffffe80
	s_add_i32 s87, s86, 0x180
	s_waitcnt lgkmcnt(2)
	v_mfma_f32_32x32x16_bf16 v[16:31], v[16:19], v[20:23], 0
	s_and_b64 s[96:97], s[48:49], exec
	s_cselect_b32 s10, s10, s87
	s_add_u32 s96, s46, s10
	s_addc_u32 s97, 0, s47
	s_waitcnt lgkmcnt(0)
	v_mfma_f32_32x32x16_bf16 v[16:31], v[32:35], v[36:39], v[16:31]
	ds_read_b128 v[32:35], v209 offset:53312
	ds_read_b128 v[36:39], v210 offset:62528
	ds_read_b128 v[40:43], v209 offset:53344
	ds_read_b128 v[44:47], v210 offset:62560
	s_waitcnt lgkmcnt(2)
	v_mfma_f32_32x32x16_bf16 v[16:31], v[32:35], v[36:39], v[16:31]
	ds_read_b128 v[32:35], v206 offset:17408
	ds_read_b128 v[36:39], v207
	ds_read_b128 v[214:217], v206 offset:17440
	ds_read_b128 v[218:221], v207 offset:32
	s_waitcnt lgkmcnt(4)
	v_mfma_f32_32x32x16_bf16 v[16:31], v[40:43], v[44:47], v[16:31]
	s_waitcnt lgkmcnt(2)
	v_mfma_f32_32x32x16_bf16 v[32:47], v[32:35], v[36:39], 0
	s_waitcnt lgkmcnt(0)
	v_mfma_f32_32x32x16_bf16 v[32:47], v[214:217], v[218:221], v[32:47]
	ds_read_b128 v[214:217], v206 offset:17472
	ds_read_b128 v[218:221], v207 offset:64
	ds_read_b128 v[222:225], v206 offset:17504
	ds_read_b128 v[226:229], v207 offset:96
	s_waitcnt lgkmcnt(2)
	v_mfma_f32_32x32x16_bf16 v[32:47], v[214:217], v[218:221], v[32:47]
	s_waitcnt lgkmcnt(0)
	v_mfma_f32_32x32x16_bf16 v[32:47], v[222:225], v[226:229], v[32:47]
	ds_read_b128 v[214:217], v206 offset:17536
	ds_read_b128 v[218:221], v207 offset:128
	ds_read_b128 v[222:225], v206 offset:17568
	ds_read_b128 v[226:229], v207 offset:160
	s_waitcnt lgkmcnt(2)
	v_mfma_f32_32x32x16_bf16 v[32:47], v[214:217], v[218:221], v[32:47]
	s_waitcnt lgkmcnt(0)
	v_mfma_f32_32x32x16_bf16 v[32:47], v[222:225], v[226:229], v[32:47]
	ds_read_b128 v[214:217], v206 offset:17600
	ds_read_b128 v[218:221], v207 offset:192
	ds_read_b128 v[222:225], v206 offset:17632
	ds_read_b128 v[226:229], v207 offset:224
	s_waitcnt lgkmcnt(2)
	v_mfma_f32_32x32x16_bf16 v[32:47], v[214:217], v[218:221], v[32:47]
	v_lshl_add_u64 v[214:215], s[96:97], 0, v[152:153]
	v_lshlrev_b64 v[214:215], 11, v[214:215]
	v_lshl_add_u64 v[214:215], v[150:151], 0, v[214:215]
	s_waitcnt lgkmcnt(0)
	v_mfma_f32_32x32x16_bf16 v[32:47], v[222:225], v[226:229], v[32:47]
	s_nop 11
	v_add_f32_e32 v16, v16, v32
	v_cvt_pk_bf16_f32 v16, v16, s0
	global_store_short v[214:215], v16, off
	v_add_f32_e32 v16, v17, v33
	v_cvt_pk_bf16_f32 v32, v16, s0
	v_lshl_add_u64 v[16:17], s[96:97], 0, v[154:155]
	v_lshlrev_b64 v[16:17], 11, v[16:17]
	v_lshl_add_u64 v[16:17], v[150:151], 0, v[16:17]
	global_store_short v[16:17], v32, off
	v_add_f32_e32 v16, v18, v34
	v_cvt_pk_bf16_f32 v18, v16, s0
	v_lshl_add_u64 v[16:17], s[96:97], 0, v[156:157]
	v_lshlrev_b64 v[16:17], 11, v[16:17]
	v_lshl_add_u64 v[16:17], v[150:151], 0, v[16:17]
	global_store_short v[16:17], v18, off
	v_add_f32_e32 v16, v19, v35
	v_cvt_pk_bf16_f32 v18, v16, s0
	v_lshl_add_u64 v[16:17], s[96:97], 0, v[158:159]
	v_lshlrev_b64 v[16:17], 11, v[16:17]
	v_lshl_add_u64 v[16:17], v[150:151], 0, v[16:17]
	global_store_short v[16:17], v18, off
	v_add_f32_e32 v16, v20, v36
	v_cvt_pk_bf16_f32 v18, v16, s0
	v_lshl_add_u64 v[16:17], s[96:97], 0, v[160:161]
	v_lshlrev_b64 v[16:17], 11, v[16:17]
	v_lshl_add_u64 v[16:17], v[150:151], 0, v[16:17]
	global_store_short v[16:17], v18, off
	v_add_f32_e32 v16, v21, v37
	v_cvt_pk_bf16_f32 v18, v16, s0
	v_lshl_add_u64 v[16:17], s[96:97], 0, v[162:163]
	v_lshlrev_b64 v[16:17], 11, v[16:17]
	v_lshl_add_u64 v[16:17], v[150:151], 0, v[16:17]
	global_store_short v[16:17], v18, off
	v_add_f32_e32 v16, v22, v38
	v_cvt_pk_bf16_f32 v18, v16, s0
	v_lshl_add_u64 v[16:17], s[96:97], 0, v[164:165]
	v_lshlrev_b64 v[16:17], 11, v[16:17]
	v_lshl_add_u64 v[16:17], v[150:151], 0, v[16:17]
	global_store_short v[16:17], v18, off
	v_add_f32_e32 v16, v23, v39
	v_cvt_pk_bf16_f32 v18, v16, s0
	v_lshl_add_u64 v[16:17], s[96:97], 0, v[166:167]
	v_lshlrev_b64 v[16:17], 11, v[16:17]
	v_lshl_add_u64 v[16:17], v[150:151], 0, v[16:17]
	global_store_short v[16:17], v18, off
	v_add_f32_e32 v16, v24, v40
	v_cvt_pk_bf16_f32 v18, v16, s0
	v_lshl_add_u64 v[16:17], s[96:97], 0, v[168:169]
	v_lshlrev_b64 v[16:17], 11, v[16:17]
	v_lshl_add_u64 v[16:17], v[150:151], 0, v[16:17]
	global_store_short v[16:17], v18, off
	v_add_f32_e32 v16, v25, v41
	v_cvt_pk_bf16_f32 v18, v16, s0
	v_lshl_add_u64 v[16:17], s[96:97], 0, v[170:171]
	v_lshlrev_b64 v[16:17], 11, v[16:17]
	v_lshl_add_u64 v[16:17], v[150:151], 0, v[16:17]
	global_store_short v[16:17], v18, off
	v_add_f32_e32 v16, v26, v42
	v_cvt_pk_bf16_f32 v18, v16, s0
	v_lshl_add_u64 v[16:17], s[96:97], 0, v[172:173]
	v_lshlrev_b64 v[16:17], 11, v[16:17]
	v_lshl_add_u64 v[16:17], v[150:151], 0, v[16:17]
	global_store_short v[16:17], v18, off
	v_add_f32_e32 v16, v27, v43
	v_cvt_pk_bf16_f32 v18, v16, s0
	v_lshl_add_u64 v[16:17], s[96:97], 0, v[174:175]
	v_lshlrev_b64 v[16:17], 11, v[16:17]
	v_lshl_add_u64 v[16:17], v[150:151], 0, v[16:17]
	global_store_short v[16:17], v18, off
	v_add_f32_e32 v16, v28, v44
	v_cvt_pk_bf16_f32 v18, v16, s0
	v_lshl_add_u64 v[16:17], s[96:97], 0, v[176:177]
	v_lshlrev_b64 v[16:17], 11, v[16:17]
	v_lshl_add_u64 v[16:17], v[150:151], 0, v[16:17]
	global_store_short v[16:17], v18, off
	v_add_f32_e32 v16, v29, v45
	v_cvt_pk_bf16_f32 v18, v16, s0
	v_lshl_add_u64 v[16:17], s[96:97], 0, v[178:179]
	v_lshlrev_b64 v[16:17], 11, v[16:17]
	v_lshl_add_u64 v[16:17], v[150:151], 0, v[16:17]
	global_store_short v[16:17], v18, off
	v_add_f32_e32 v16, v30, v46
	v_cvt_pk_bf16_f32 v18, v16, s0
	v_lshl_add_u64 v[16:17], s[96:97], 0, v[180:181]
	v_lshlrev_b64 v[16:17], 11, v[16:17]
	v_lshl_add_u64 v[16:17], v[150:151], 0, v[16:17]
	global_store_short v[16:17], v18, off
	v_add_f32_e32 v16, v31, v47
	v_cvt_pk_bf16_f32 v18, v16, s0
	v_lshl_add_u64 v[16:17], s[96:97], 0, v[182:183]
	v_lshlrev_b64 v[16:17], 11, v[16:17]
	v_lshl_add_u64 v[16:17], v[150:151], 0, v[16:17]
	global_store_short v[16:17], v18, off

.LBB0_488:
	s_or_b64 exec, exec, s[52:53]
	s_add_i32 s10, s85, 0xffffff80
	s_add_i32 s87, s86, 0x80
	s_and_b64 s[52:53], s[48:49], exec
	s_cselect_b32 s10, s10, s87
	v_lshl_add_u64 v[16:17], v[148:149], 0, s[10:11]
	v_lshlrev_b64 v[16:17], 11, v[16:17]
	v_lshl_add_u64 v[16:17], v[146:147], 0, v[16:17]
	global_load_dwordx4 v[120:123], v[16:17], off
	s_waitcnt vmcnt(23)
	ds_write_b128 v202, v[88:91] offset:17408
	s_waitcnt vmcnt(22)
	ds_write_b128 v202, v[92:95] offset:17424
	s_waitcnt vmcnt(21)
	ds_write_b128 v203, v[100:103] offset:34816
	s_waitcnt vmcnt(20)
	ds_write_b128 v203, v[104:107] offset:34832
	s_waitcnt vmcnt(19)
	ds_write_b128 v204, v[108:111] offset:53248
	s_waitcnt vmcnt(18)
	s_branch .Lsw1_join

.Lsw1_join:
	ds_write_b16 v144, v136 offset:62464
	ds_write_b16_d16_hi v144, v136 offset:62608
	ds_write_b16 v144, v137 offset:62752
	ds_write_b16_d16_hi v144, v137 offset:62896
	ds_write_b16 v144, v138 offset:63040
	ds_write_b16_d16_hi v144, v138 offset:63184
	ds_write_b16 v144, v139 offset:63328
	ds_write_b16_d16_hi v144, v139 offset:63472
	s_and_saveexec_b64 s[52:53], s[0:1]
	ds_write_b32 v205, v201
	s_or_b64 exec, exec, s[52:53]
	s_waitcnt lgkmcnt(0)
	s_barrier
	s_and_saveexec_b64 s[52:53], s[4:5]
	s_cbranch_execz .LBB0_493
	ds_read_b128 v[16:19], v209 offset:53248
	ds_read_b128 v[20:23], v210 offset:62464
	ds_read_b128 v[32:35], v209 offset:53280
	ds_read_b128 v[36:39], v210 offset:62496
	s_add_i32 s10, s85, 0xfffffec0
	s_add_i32 s87, s86, 0x140
	s_waitcnt lgkmcnt(2)
	v_mfma_f32_32x32x16_bf16 v[16:31], v[16:19], v[20:23], 0
	s_and_b64 s[96:97], s[48:49], exec
	s_cselect_b32 s10, s10, s87
	s_add_u32 s96, s46, s10
	s_addc_u32 s97, 0, s47
	s_waitcnt lgkmcnt(0)
	v_mfma_f32_32x32x16_bf16 v[16:31], v[32:35], v[36:39], v[16:31]
	ds_read_b128 v[32:35], v209 offset:53312
	ds_read_b128 v[36:39], v210 offset:62528
	ds_read_b128 v[40:43], v209 offset:53344
	ds_read_b128 v[44:47], v210 offset:62560
	s_waitcnt lgkmcnt(2)
	v_mfma_f32_32x32x16_bf16 v[16:31], v[32:35], v[36:39], v[16:31]
	ds_read_b128 v[32:35], v206 offset:17408
	ds_read_b128 v[36:39], v207
	ds_read_b128 v[214:217], v206 offset:17440
	ds_read_b128 v[218:221], v207 offset:32
	s_waitcnt lgkmcnt(4)
	v_mfma_f32_32x32x16_bf16 v[16:31], v[40:43], v[44:47], v[16:31]
	s_waitcnt lgkmcnt(2)
	v_mfma_f32_32x32x16_bf16 v[32:47], v[32:35], v[36:39], 0
	s_waitcnt lgkmcnt(0)
	v_mfma_f32_32x32x16_bf16 v[32:47], v[214:217], v[218:221], v[32:47]
	ds_read_b128 v[214:217], v206 offset:17472
	ds_read_b128 v[218:221], v207 offset:64
	ds_read_b128 v[222:225], v206 offset:17504
	ds_read_b128 v[226:229], v207 offset:96
	s_waitcnt lgkmcnt(2)
	v_mfma_f32_32x32x16_bf16 v[32:47], v[214:217], v[218:221], v[32:47]
	s_waitcnt lgkmcnt(0)
	v_mfma_f32_32x32x16_bf16 v[32:47], v[222:225], v[226:229], v[32:47]
	ds_read_b128 v[214:217], v206 offset:17536
	ds_read_b128 v[218:221], v207 offset:128
	ds_read_b128 v[222:225], v206 offset:17568
	ds_read_b128 v[226:229], v207 offset:160
	s_waitcnt lgkmcnt(2)
	v_mfma_f32_32x32x16_bf16 v[32:47], v[214:217], v[218:221], v[32:47]
	s_waitcnt lgkmcnt(0)
	v_mfma_f32_32x32x16_bf16 v[32:47], v[222:225], v[226:229], v[32:47]
	ds_read_b128 v[214:217], v206 offset:17600
	ds_read_b128 v[218:221], v207 offset:192
	ds_read_b128 v[222:225], v206 offset:17632
	ds_read_b128 v[226:229], v207 offset:224
	s_waitcnt lgkmcnt(2)
	v_mfma_f32_32x32x16_bf16 v[32:47], v[214:217], v[218:221], v[32:47]
	v_lshl_add_u64 v[214:215], s[96:97], 0, v[152:153]
	v_lshlrev_b64 v[214:215], 11, v[214:215]
	v_lshl_add_u64 v[214:215], v[150:151], 0, v[214:215]
	s_waitcnt lgkmcnt(0)
	v_mfma_f32_32x32x16_bf16 v[32:47], v[222:225], v[226:229], v[32:47]
	s_nop 11
	v_add_f32_e32 v16, v16, v32
	v_cvt_pk_bf16_f32 v16, v16, s0
	global_store_short v[214:215], v16, off
	v_add_f32_e32 v16, v17, v33
	v_cvt_pk_bf16_f32 v32, v16, s0
	v_lshl_add_u64 v[16:17], s[96:97], 0, v[154:155]
	v_lshlrev_b64 v[16:17], 11, v[16:17]
	v_lshl_add_u64 v[16:17], v[150:151], 0, v[16:17]
	global_store_short v[16:17], v32, off
	v_add_f32_e32 v16, v18, v34
	v_cvt_pk_bf16_f32 v18, v16, s0
	v_lshl_add_u64 v[16:17], s[96:97], 0, v[156:157]
	v_lshlrev_b64 v[16:17], 11, v[16:17]
	v_lshl_add_u64 v[16:17], v[150:151], 0, v[16:17]
	global_store_short v[16:17], v18, off
	v_add_f32_e32 v16, v19, v35
	v_cvt_pk_bf16_f32 v18, v16, s0
	v_lshl_add_u64 v[16:17], s[96:97], 0, v[158:159]
	v_lshlrev_b64 v[16:17], 11, v[16:17]
	v_lshl_add_u64 v[16:17], v[150:151], 0, v[16:17]
	global_store_short v[16:17], v18, off
	v_add_f32_e32 v16, v20, v36
	v_cvt_pk_bf16_f32 v18, v16, s0
	v_lshl_add_u64 v[16:17], s[96:97], 0, v[160:161]
	v_lshlrev_b64 v[16:17], 11, v[16:17]
	v_lshl_add_u64 v[16:17], v[150:151], 0, v[16:17]
	global_store_short v[16:17], v18, off
	v_add_f32_e32 v16, v21, v37
	v_cvt_pk_bf16_f32 v18, v16, s0
	v_lshl_add_u64 v[16:17], s[96:97], 0, v[162:163]
	v_lshlrev_b64 v[16:17], 11, v[16:17]
	v_lshl_add_u64 v[16:17], v[150:151], 0, v[16:17]
	global_store_short v[16:17], v18, off
	v_add_f32_e32 v16, v22, v38
	v_cvt_pk_bf16_f32 v18, v16, s0
	v_lshl_add_u64 v[16:17], s[96:97], 0, v[164:165]
	v_lshlrev_b64 v[16:17], 11, v[16:17]
	v_lshl_add_u64 v[16:17], v[150:151], 0, v[16:17]
	global_store_short v[16:17], v18, off
	v_add_f32_e32 v16, v23, v39
	v_cvt_pk_bf16_f32 v18, v16, s0
	v_lshl_add_u64 v[16:17], s[96:97], 0, v[166:167]
	v_lshlrev_b64 v[16:17], 11, v[16:17]
	v_lshl_add_u64 v[16:17], v[150:151], 0, v[16:17]
	global_store_short v[16:17], v18, off
	v_add_f32_e32 v16, v24, v40
	v_cvt_pk_bf16_f32 v18, v16, s0
	v_lshl_add_u64 v[16:17], s[96:97], 0, v[168:169]
	v_lshlrev_b64 v[16:17], 11, v[16:17]
	v_lshl_add_u64 v[16:17], v[150:151], 0, v[16:17]
	global_store_short v[16:17], v18, off
	v_add_f32_e32 v16, v25, v41
	v_cvt_pk_bf16_f32 v18, v16, s0
	v_lshl_add_u64 v[16:17], s[96:97], 0, v[170:171]
	v_lshlrev_b64 v[16:17], 11, v[16:17]
	v_lshl_add_u64 v[16:17], v[150:151], 0, v[16:17]
	global_store_short v[16:17], v18, off
	v_add_f32_e32 v16, v26, v42
	v_cvt_pk_bf16_f32 v18, v16, s0
	v_lshl_add_u64 v[16:17], s[96:97], 0, v[172:173]
	v_lshlrev_b64 v[16:17], 11, v[16:17]
	v_lshl_add_u64 v[16:17], v[150:151], 0, v[16:17]
	global_store_short v[16:17], v18, off
	v_add_f32_e32 v16, v27, v43
	v_cvt_pk_bf16_f32 v18, v16, s0
	v_lshl_add_u64 v[16:17], s[96:97], 0, v[174:175]
	v_lshlrev_b64 v[16:17], 11, v[16:17]
	v_lshl_add_u64 v[16:17], v[150:151], 0, v[16:17]
	global_store_short v[16:17], v18, off
	v_add_f32_e32 v16, v28, v44
	v_cvt_pk_bf16_f32 v18, v16, s0
	v_lshl_add_u64 v[16:17], s[96:97], 0, v[176:177]
	v_lshlrev_b64 v[16:17], 11, v[16:17]
	v_lshl_add_u64 v[16:17], v[150:151], 0, v[16:17]
	global_store_short v[16:17], v18, off
	v_add_f32_e32 v16, v29, v45
	v_cvt_pk_bf16_f32 v18, v16, s0
	v_lshl_add_u64 v[16:17], s[96:97], 0, v[178:179]
	v_lshlrev_b64 v[16:17], 11, v[16:17]
	v_lshl_add_u64 v[16:17], v[150:151], 0, v[16:17]
	global_store_short v[16:17], v18, off
	v_add_f32_e32 v16, v30, v46
	v_cvt_pk_bf16_f32 v18, v16, s0
	v_lshl_add_u64 v[16:17], s[96:97], 0, v[180:181]
	v_lshlrev_b64 v[16:17], 11, v[16:17]
	v_lshl_add_u64 v[16:17], v[150:151], 0, v[16:17]
	global_store_short v[16:17], v18, off
	v_add_f32_e32 v16, v31, v47
	v_cvt_pk_bf16_f32 v18, v16, s0
	v_lshl_add_u64 v[16:17], s[96:97], 0, v[182:183]
	v_lshlrev_b64 v[16:17], 11, v[16:17]
	v_lshl_add_u64 v[16:17], v[150:151], 0, v[16:17]
	global_store_short v[16:17], v18, off

.LBB0_496:
	s_or_b64 exec, exec, s[52:53]
	s_sub_i32 s10, s85, 64
	s_add_i32 s87, s86, 64
	s_and_b64 s[52:53], s[48:49], exec
	s_cselect_b32 s10, s10, s87
	v_lshl_add_u64 v[16:17], v[148:149], 0, s[10:11]
	v_lshlrev_b64 v[16:17], 11, v[16:17]
	v_lshl_add_u64 v[16:17], v[146:147], 0, v[16:17]
	global_load_dwordx4 v[136:139], v[16:17], off
	s_waitcnt vmcnt(23)
	ds_write_b128 v202, v[112:115] offset:17408
	s_waitcnt vmcnt(22)
	ds_write_b128 v202, v[116:119] offset:17424
	s_waitcnt vmcnt(21)
	ds_write_b128 v203, v[124:127] offset:34816
	s_waitcnt vmcnt(20)
	ds_write_b128 v203, v[128:131] offset:34832
	s_waitcnt vmcnt(19)
	ds_write_b128 v204, v[132:135] offset:53248
	s_waitcnt vmcnt(18)
	s_branch .Lsw2_join

.Lsw2_join:
	ds_write_b16 v144, v140 offset:62464
	ds_write_b16_d16_hi v144, v140 offset:62608
	ds_write_b16 v144, v141 offset:62752
	ds_write_b16_d16_hi v144, v141 offset:62896
	ds_write_b16 v144, v142 offset:63040
	ds_write_b16_d16_hi v144, v142 offset:63184
	ds_write_b16 v144, v143 offset:63328
	ds_write_b16_d16_hi v144, v143 offset:63472
	s_and_saveexec_b64 s[52:53], s[0:1]
	ds_write_b32 v205, v200
	s_or_b64 exec, exec, s[52:53]
	s_waitcnt lgkmcnt(0)
	s_barrier
	s_and_saveexec_b64 s[52:53], s[4:5]
	s_cbranch_execz .LBB0_501
	ds_read_b128 v[16:19], v209 offset:53248
	ds_read_b128 v[20:23], v210 offset:62464
	ds_read_b128 v[32:35], v209 offset:53280
	ds_read_b128 v[36:39], v210 offset:62496
	s_add_i32 s10, s85, 0xffffff00
	s_add_i32 s87, s86, 0x100
	s_waitcnt lgkmcnt(2)
	v_mfma_f32_32x32x16_bf16 v[16:31], v[16:19], v[20:23], 0
	s_and_b64 s[96:97], s[48:49], exec
	s_cselect_b32 s10, s10, s87
	s_add_u32 s96, s46, s10
	s_addc_u32 s97, 0, s47
	s_waitcnt lgkmcnt(0)
	v_mfma_f32_32x32x16_bf16 v[16:31], v[32:35], v[36:39], v[16:31]
	ds_read_b128 v[32:35], v209 offset:53312
	ds_read_b128 v[36:39], v210 offset:62528
	ds_read_b128 v[40:43], v209 offset:53344
	ds_read_b128 v[44:47], v210 offset:62560
	s_waitcnt lgkmcnt(2)
	v_mfma_f32_32x32x16_bf16 v[16:31], v[32:35], v[36:39], v[16:31]
	ds_read_b128 v[32:35], v206 offset:17408
	ds_read_b128 v[36:39], v207
	ds_read_b128 v[214:217], v206 offset:17440
	ds_read_b128 v[218:221], v207 offset:32
	s_waitcnt lgkmcnt(4)
	v_mfma_f32_32x32x16_bf16 v[16:31], v[40:43], v[44:47], v[16:31]
	s_waitcnt lgkmcnt(2)
	v_mfma_f32_32x32x16_bf16 v[32:47], v[32:35], v[36:39], 0
	s_waitcnt lgkmcnt(0)
	v_mfma_f32_32x32x16_bf16 v[32:47], v[214:217], v[218:221], v[32:47]
	ds_read_b128 v[214:217], v206 offset:17472
	ds_read_b128 v[218:221], v207 offset:64
	ds_read_b128 v[222:225], v206 offset:17504
	ds_read_b128 v[226:229], v207 offset:96
	s_waitcnt lgkmcnt(2)
	v_mfma_f32_32x32x16_bf16 v[32:47], v[214:217], v[218:221], v[32:47]
	s_waitcnt lgkmcnt(0)
	v_mfma_f32_32x32x16_bf16 v[32:47], v[222:225], v[226:229], v[32:47]
	ds_read_b128 v[214:217], v206 offset:17536
	ds_read_b128 v[218:221], v207 offset:128
	ds_read_b128 v[222:225], v206 offset:17568
	ds_read_b128 v[226:229], v207 offset:160
	s_waitcnt lgkmcnt(2)
	v_mfma_f32_32x32x16_bf16 v[32:47], v[214:217], v[218:221], v[32:47]
	s_waitcnt lgkmcnt(0)
	v_mfma_f32_32x32x16_bf16 v[32:47], v[222:225], v[226:229], v[32:47]
	ds_read_b128 v[214:217], v206 offset:17600
	ds_read_b128 v[218:221], v207 offset:192
	ds_read_b128 v[222:225], v206 offset:17632
	ds_read_b128 v[226:229], v207 offset:224
	s_waitcnt lgkmcnt(2)
	v_mfma_f32_32x32x16_bf16 v[32:47], v[214:217], v[218:221], v[32:47]
	v_lshl_add_u64 v[214:215], s[96:97], 0, v[152:153]
	v_lshlrev_b64 v[214:215], 11, v[214:215]
	v_lshl_add_u64 v[214:215], v[150:151], 0, v[214:215]
	s_waitcnt lgkmcnt(0)
	v_mfma_f32_32x32x16_bf16 v[32:47], v[222:225], v[226:229], v[32:47]
	s_nop 11
	v_add_f32_e32 v16, v16, v32
	v_cvt_pk_bf16_f32 v16, v16, s0
	global_store_short v[214:215], v16, off
	v_add_f32_e32 v16, v17, v33
	v_cvt_pk_bf16_f32 v32, v16, s0
	v_lshl_add_u64 v[16:17], s[96:97], 0, v[154:155]
	v_lshlrev_b64 v[16:17], 11, v[16:17]
	v_lshl_add_u64 v[16:17], v[150:151], 0, v[16:17]
	global_store_short v[16:17], v32, off
	v_add_f32_e32 v16, v18, v34
	v_cvt_pk_bf16_f32 v18, v16, s0
	v_lshl_add_u64 v[16:17], s[96:97], 0, v[156:157]
	v_lshlrev_b64 v[16:17], 11, v[16:17]
	v_lshl_add_u64 v[16:17], v[150:151], 0, v[16:17]
	global_store_short v[16:17], v18, off
	v_add_f32_e32 v16, v19, v35
	v_cvt_pk_bf16_f32 v18, v16, s0
	v_lshl_add_u64 v[16:17], s[96:97], 0, v[158:159]
	v_lshlrev_b64 v[16:17], 11, v[16:17]
	v_lshl_add_u64 v[16:17], v[150:151], 0, v[16:17]
	global_store_short v[16:17], v18, off
	v_add_f32_e32 v16, v20, v36
	v_cvt_pk_bf16_f32 v18, v16, s0
	v_lshl_add_u64 v[16:17], s[96:97], 0, v[160:161]
	v_lshlrev_b64 v[16:17], 11, v[16:17]
	v_lshl_add_u64 v[16:17], v[150:151], 0, v[16:17]
	global_store_short v[16:17], v18, off
	v_add_f32_e32 v16, v21, v37
	v_cvt_pk_bf16_f32 v18, v16, s0
	v_lshl_add_u64 v[16:17], s[96:97], 0, v[162:163]
	v_lshlrev_b64 v[16:17], 11, v[16:17]
	v_lshl_add_u64 v[16:17], v[150:151], 0, v[16:17]
	global_store_short v[16:17], v18, off
	v_add_f32_e32 v16, v22, v38
	v_cvt_pk_bf16_f32 v18, v16, s0
	v_lshl_add_u64 v[16:17], s[96:97], 0, v[164:165]
	v_lshlrev_b64 v[16:17], 11, v[16:17]
	v_lshl_add_u64 v[16:17], v[150:151], 0, v[16:17]
	global_store_short v[16:17], v18, off
	v_add_f32_e32 v16, v23, v39
	v_cvt_pk_bf16_f32 v18, v16, s0
	v_lshl_add_u64 v[16:17], s[96:97], 0, v[166:167]
	v_lshlrev_b64 v[16:17], 11, v[16:17]
	v_lshl_add_u64 v[16:17], v[150:151], 0, v[16:17]
	global_store_short v[16:17], v18, off
	v_add_f32_e32 v16, v24, v40
	v_cvt_pk_bf16_f32 v18, v16, s0
	v_lshl_add_u64 v[16:17], s[96:97], 0, v[168:169]
	v_lshlrev_b64 v[16:17], 11, v[16:17]
	v_lshl_add_u64 v[16:17], v[150:151], 0, v[16:17]
	global_store_short v[16:17], v18, off
	v_add_f32_e32 v16, v25, v41
	v_cvt_pk_bf16_f32 v18, v16, s0
	v_lshl_add_u64 v[16:17], s[96:97], 0, v[170:171]
	v_lshlrev_b64 v[16:17], 11, v[16:17]
	v_lshl_add_u64 v[16:17], v[150:151], 0, v[16:17]
	global_store_short v[16:17], v18, off
	v_add_f32_e32 v16, v26, v42
	v_cvt_pk_bf16_f32 v18, v16, s0
	v_lshl_add_u64 v[16:17], s[96:97], 0, v[172:173]
	v_lshlrev_b64 v[16:17], 11, v[16:17]
	v_lshl_add_u64 v[16:17], v[150:151], 0, v[16:17]
	global_store_short v[16:17], v18, off
	v_add_f32_e32 v16, v27, v43
	v_cvt_pk_bf16_f32 v18, v16, s0
	v_lshl_add_u64 v[16:17], s[96:97], 0, v[174:175]
	v_lshlrev_b64 v[16:17], 11, v[16:17]
	v_lshl_add_u64 v[16:17], v[150:151], 0, v[16:17]
	global_store_short v[16:17], v18, off
	v_add_f32_e32 v16, v28, v44
	v_cvt_pk_bf16_f32 v18, v16, s0
	v_lshl_add_u64 v[16:17], s[96:97], 0, v[176:177]
	v_lshlrev_b64 v[16:17], 11, v[16:17]
	v_lshl_add_u64 v[16:17], v[150:151], 0, v[16:17]
	global_store_short v[16:17], v18, off
	v_add_f32_e32 v16, v29, v45
	v_cvt_pk_bf16_f32 v18, v16, s0
	v_lshl_add_u64 v[16:17], s[96:97], 0, v[178:179]
	v_lshlrev_b64 v[16:17], 11, v[16:17]
	v_lshl_add_u64 v[16:17], v[150:151], 0, v[16:17]
	global_store_short v[16:17], v18, off
	v_add_f32_e32 v16, v30, v46
	v_cvt_pk_bf16_f32 v18, v16, s0
	v_lshl_add_u64 v[16:17], s[96:97], 0, v[180:181]
	v_lshlrev_b64 v[16:17], 11, v[16:17]
	v_lshl_add_u64 v[16:17], v[150:151], 0, v[16:17]
	global_store_short v[16:17], v18, off
	v_add_f32_e32 v16, v31, v47
	v_cvt_pk_bf16_f32 v18, v16, s0
	v_lshl_add_u64 v[16:17], s[96:97], 0, v[182:183]
	v_lshlrev_b64 v[16:17], 11, v[16:17]
	v_lshl_add_u64 v[16:17], v[150:151], 0, v[16:17]
	global_store_short v[16:17], v18, off

.LBB0_873:
	s_or_b64 exec, exec, s[52:53]
	s_add_i32 s10, s79, 0xffffff40
	s_add_i32 s81, s80, 0xc0
	s_and_b64 s[52:53], s[48:49], exec
	s_cselect_b32 s10, s10, s81
	v_lshl_add_u64 v[16:17], v[148:149], 0, s[10:11]
	v_lshlrev_b64 v[16:17], 11, v[16:17]
	v_lshl_add_u64 v[16:17], v[146:147], 0, v[16:17]
	global_load_dwordx4 v[96:99], v[16:17], off
	s_waitcnt vmcnt(23)
	ds_write_b128 v202, v[68:71] offset:17408
	s_waitcnt vmcnt(22)
	ds_write_b128 v202, v[72:75] offset:17424
	s_waitcnt vmcnt(21)
	ds_write_b128 v203, v[76:79] offset:34816
	s_waitcnt vmcnt(20)
	ds_write_b128 v203, v[80:83] offset:34832
	s_waitcnt vmcnt(19)
	ds_write_b128 v204, v[84:87] offset:53248
	s_waitcnt vmcnt(18)
	s_branch .Lsw3_join

.Lsw3_join:
	ds_write_b16 v144, v120 offset:62464
	ds_write_b16_d16_hi v144, v120 offset:62608
	ds_write_b16 v144, v121 offset:62752
	ds_write_b16_d16_hi v144, v121 offset:62896
	ds_write_b16 v144, v122 offset:63040
	ds_write_b16_d16_hi v144, v122 offset:63184
	ds_write_b16 v144, v123 offset:63328
	ds_write_b16_d16_hi v144, v123 offset:63472
	s_and_saveexec_b64 s[52:53], s[0:1]
	ds_write_b32 v205, v198
	s_or_b64 exec, exec, s[52:53]
	s_waitcnt lgkmcnt(0)
	s_barrier
	s_and_saveexec_b64 s[52:53], s[4:5]
	s_cbranch_execz .LBB0_878
	ds_read_b128 v[16:19], v209 offset:53248
	ds_read_b128 v[20:23], v210 offset:62464
	ds_read_b128 v[32:35], v209 offset:53280
	ds_read_b128 v[36:39], v210 offset:62496
	s_add_i32 s10, s79, 0xfffffe80
	s_add_i32 s81, s80, 0x180
	s_waitcnt lgkmcnt(2)
	v_mfma_f32_32x32x16_bf16 v[16:31], v[16:19], v[20:23], 0
	s_and_b64 s[84:85], s[48:49], exec
	s_cselect_b32 s10, s10, s81
	s_add_u32 s84, s46, s10
	s_addc_u32 s85, 0, s47
	s_waitcnt lgkmcnt(0)
	v_mfma_f32_32x32x16_bf16 v[16:31], v[32:35], v[36:39], v[16:31]
	ds_read_b128 v[32:35], v209 offset:53312
	ds_read_b128 v[36:39], v210 offset:62528
	ds_read_b128 v[40:43], v209 offset:53344
	ds_read_b128 v[44:47], v210 offset:62560
	s_waitcnt lgkmcnt(2)
	v_mfma_f32_32x32x16_bf16 v[16:31], v[32:35], v[36:39], v[16:31]
	ds_read_b128 v[32:35], v206 offset:17408
	ds_read_b128 v[36:39], v207
	ds_read_b128 v[214:217], v206 offset:17440
	ds_read_b128 v[218:221], v207 offset:32
	s_waitcnt lgkmcnt(4)
	v_mfma_f32_32x32x16_bf16 v[16:31], v[40:43], v[44:47], v[16:31]
	s_waitcnt lgkmcnt(2)
	v_mfma_f32_32x32x16_bf16 v[32:47], v[32:35], v[36:39], 0
	s_waitcnt lgkmcnt(0)
	v_mfma_f32_32x32x16_bf16 v[32:47], v[214:217], v[218:221], v[32:47]
	ds_read_b128 v[214:217], v206 offset:17472
	ds_read_b128 v[218:221], v207 offset:64
	ds_read_b128 v[222:225], v206 offset:17504
	ds_read_b128 v[226:229], v207 offset:96
	s_waitcnt lgkmcnt(2)
	v_mfma_f32_32x32x16_bf16 v[32:47], v[214:217], v[218:221], v[32:47]
	s_waitcnt lgkmcnt(0)
	v_mfma_f32_32x32x16_bf16 v[32:47], v[222:225], v[226:229], v[32:47]
	ds_read_b128 v[214:217], v206 offset:17536
	ds_read_b128 v[218:221], v207 offset:128
	ds_read_b128 v[222:225], v206 offset:17568
	ds_read_b128 v[226:229], v207 offset:160
	s_waitcnt lgkmcnt(2)
	v_mfma_f32_32x32x16_bf16 v[32:47], v[214:217], v[218:221], v[32:47]
	s_waitcnt lgkmcnt(0)
	v_mfma_f32_32x32x16_bf16 v[32:47], v[222:225], v[226:229], v[32:47]
	ds_read_b128 v[214:217], v206 offset:17600
	ds_read_b128 v[218:221], v207 offset:192
	ds_read_b128 v[222:225], v206 offset:17632
	ds_read_b128 v[226:229], v207 offset:224
	s_waitcnt lgkmcnt(2)
	v_mfma_f32_32x32x16_bf16 v[32:47], v[214:217], v[218:221], v[32:47]
	v_lshl_add_u64 v[214:215], s[84:85], 0, v[152:153]
	v_lshlrev_b64 v[214:215], 11, v[214:215]
	v_lshl_add_u64 v[214:215], v[150:151], 0, v[214:215]
	s_waitcnt lgkmcnt(0)
	v_mfma_f32_32x32x16_bf16 v[32:47], v[222:225], v[226:229], v[32:47]
	s_nop 11
	v_add_f32_e32 v16, v16, v32
	v_cvt_pk_bf16_f32 v16, v16, s0
	global_store_short v[214:215], v16, off
	v_add_f32_e32 v16, v17, v33
	v_cvt_pk_bf16_f32 v32, v16, s0
	v_lshl_add_u64 v[16:17], s[84:85], 0, v[154:155]
	v_lshlrev_b64 v[16:17], 11, v[16:17]
	v_lshl_add_u64 v[16:17], v[150:151], 0, v[16:17]
	global_store_short v[16:17], v32, off
	v_add_f32_e32 v16, v18, v34
	v_cvt_pk_bf16_f32 v18, v16, s0
	v_lshl_add_u64 v[16:17], s[84:85], 0, v[156:157]
	v_lshlrev_b64 v[16:17], 11, v[16:17]
	v_lshl_add_u64 v[16:17], v[150:151], 0, v[16:17]
	global_store_short v[16:17], v18, off
	v_add_f32_e32 v16, v19, v35
	v_cvt_pk_bf16_f32 v18, v16, s0
	v_lshl_add_u64 v[16:17], s[84:85], 0, v[158:159]
	v_lshlrev_b64 v[16:17], 11, v[16:17]
	v_lshl_add_u64 v[16:17], v[150:151], 0, v[16:17]
	global_store_short v[16:17], v18, off
	v_add_f32_e32 v16, v20, v36
	v_cvt_pk_bf16_f32 v18, v16, s0
	v_lshl_add_u64 v[16:17], s[84:85], 0, v[160:161]
	v_lshlrev_b64 v[16:17], 11, v[16:17]
	v_lshl_add_u64 v[16:17], v[150:151], 0, v[16:17]
	global_store_short v[16:17], v18, off
	v_add_f32_e32 v16, v21, v37
	v_cvt_pk_bf16_f32 v18, v16, s0
	v_lshl_add_u64 v[16:17], s[84:85], 0, v[162:163]
	v_lshlrev_b64 v[16:17], 11, v[16:17]
	v_lshl_add_u64 v[16:17], v[150:151], 0, v[16:17]
	global_store_short v[16:17], v18, off
	v_add_f32_e32 v16, v22, v38
	v_cvt_pk_bf16_f32 v18, v16, s0
	v_lshl_add_u64 v[16:17], s[84:85], 0, v[164:165]
	v_lshlrev_b64 v[16:17], 11, v[16:17]
	v_lshl_add_u64 v[16:17], v[150:151], 0, v[16:17]
	global_store_short v[16:17], v18, off
	v_add_f32_e32 v16, v23, v39
	v_cvt_pk_bf16_f32 v18, v16, s0
	v_lshl_add_u64 v[16:17], s[84:85], 0, v[166:167]
	v_lshlrev_b64 v[16:17], 11, v[16:17]
	v_lshl_add_u64 v[16:17], v[150:151], 0, v[16:17]
	global_store_short v[16:17], v18, off
	v_add_f32_e32 v16, v24, v40
	v_cvt_pk_bf16_f32 v18, v16, s0
	v_lshl_add_u64 v[16:17], s[84:85], 0, v[168:169]
	v_lshlrev_b64 v[16:17], 11, v[16:17]
	v_lshl_add_u64 v[16:17], v[150:151], 0, v[16:17]
	global_store_short v[16:17], v18, off
	v_add_f32_e32 v16, v25, v41
	v_cvt_pk_bf16_f32 v18, v16, s0
	v_lshl_add_u64 v[16:17], s[84:85], 0, v[170:171]
	v_lshlrev_b64 v[16:17], 11, v[16:17]
	v_lshl_add_u64 v[16:17], v[150:151], 0, v[16:17]
	global_store_short v[16:17], v18, off
	v_add_f32_e32 v16, v26, v42
	v_cvt_pk_bf16_f32 v18, v16, s0
	v_lshl_add_u64 v[16:17], s[84:85], 0, v[172:173]
	v_lshlrev_b64 v[16:17], 11, v[16:17]
	v_lshl_add_u64 v[16:17], v[150:151], 0, v[16:17]
	global_store_short v[16:17], v18, off
	v_add_f32_e32 v16, v27, v43
	v_cvt_pk_bf16_f32 v18, v16, s0
	v_lshl_add_u64 v[16:17], s[84:85], 0, v[174:175]
	v_lshlrev_b64 v[16:17], 11, v[16:17]
	v_lshl_add_u64 v[16:17], v[150:151], 0, v[16:17]
	global_store_short v[16:17], v18, off
	v_add_f32_e32 v16, v28, v44
	v_cvt_pk_bf16_f32 v18, v16, s0
	v_lshl_add_u64 v[16:17], s[84:85], 0, v[176:177]
	v_lshlrev_b64 v[16:17], 11, v[16:17]
	v_lshl_add_u64 v[16:17], v[150:151], 0, v[16:17]
	global_store_short v[16:17], v18, off
	v_add_f32_e32 v16, v29, v45
	v_cvt_pk_bf16_f32 v18, v16, s0
	v_lshl_add_u64 v[16:17], s[84:85], 0, v[178:179]
	v_lshlrev_b64 v[16:17], 11, v[16:17]
	v_lshl_add_u64 v[16:17], v[150:151], 0, v[16:17]
	global_store_short v[16:17], v18, off
	v_add_f32_e32 v16, v30, v46
	v_cvt_pk_bf16_f32 v18, v16, s0
	v_lshl_add_u64 v[16:17], s[84:85], 0, v[180:181]
	v_lshlrev_b64 v[16:17], 11, v[16:17]
	v_lshl_add_u64 v[16:17], v[150:151], 0, v[16:17]
	global_store_short v[16:17], v18, off
	v_add_f32_e32 v16, v31, v47
	v_cvt_pk_bf16_f32 v18, v16, s0
	v_lshl_add_u64 v[16:17], s[84:85], 0, v[182:183]
	v_lshlrev_b64 v[16:17], 11, v[16:17]
	v_lshl_add_u64 v[16:17], v[150:151], 0, v[16:17]
	global_store_short v[16:17], v18, off

.LBB0_881:
	s_or_b64 exec, exec, s[52:53]
	s_add_i32 s10, s79, 0xffffff80
	s_add_i32 s81, s80, 0x80
	s_and_b64 s[52:53], s[48:49], exec
	s_cselect_b32 s10, s10, s81
	v_lshl_add_u64 v[16:17], v[148:149], 0, s[10:11]
	v_lshlrev_b64 v[16:17], 11, v[16:17]
	v_lshl_add_u64 v[16:17], v[146:147], 0, v[16:17]
	global_load_dwordx4 v[120:123], v[16:17], off
	s_waitcnt vmcnt(23)
	ds_write_b128 v202, v[88:91] offset:17408
	s_waitcnt vmcnt(22)
	ds_write_b128 v202, v[92:95] offset:17424
	s_waitcnt vmcnt(21)
	ds_write_b128 v203, v[100:103] offset:34816
	s_waitcnt vmcnt(20)
	ds_write_b128 v203, v[104:107] offset:34832
	s_waitcnt vmcnt(19)
	ds_write_b128 v204, v[108:111] offset:53248
	s_waitcnt vmcnt(18)
	s_branch .Lsw4_join

.Lsw4_join:
	ds_write_b16 v144, v136 offset:62464
	ds_write_b16_d16_hi v144, v136 offset:62608
	ds_write_b16 v144, v137 offset:62752
	ds_write_b16_d16_hi v144, v137 offset:62896
	ds_write_b16 v144, v138 offset:63040
	ds_write_b16_d16_hi v144, v138 offset:63184
	ds_write_b16 v144, v139 offset:63328
	ds_write_b16_d16_hi v144, v139 offset:63472
	s_and_saveexec_b64 s[52:53], s[0:1]
	ds_write_b32 v205, v201
	s_or_b64 exec, exec, s[52:53]
	s_waitcnt lgkmcnt(0)
	s_barrier
	s_and_saveexec_b64 s[52:53], s[4:5]
	s_cbranch_execz .LBB0_886
	ds_read_b128 v[16:19], v209 offset:53248
	ds_read_b128 v[20:23], v210 offset:62464
	ds_read_b128 v[32:35], v209 offset:53280
	ds_read_b128 v[36:39], v210 offset:62496
	s_add_i32 s10, s79, 0xfffffec0
	s_add_i32 s81, s80, 0x140
	s_waitcnt lgkmcnt(2)
	v_mfma_f32_32x32x16_bf16 v[16:31], v[16:19], v[20:23], 0
	s_and_b64 s[84:85], s[48:49], exec
	s_cselect_b32 s10, s10, s81
	s_add_u32 s84, s46, s10
	s_addc_u32 s85, 0, s47
	s_waitcnt lgkmcnt(0)
	v_mfma_f32_32x32x16_bf16 v[16:31], v[32:35], v[36:39], v[16:31]
	ds_read_b128 v[32:35], v209 offset:53312
	ds_read_b128 v[36:39], v210 offset:62528
	ds_read_b128 v[40:43], v209 offset:53344
	ds_read_b128 v[44:47], v210 offset:62560
	s_waitcnt lgkmcnt(2)
	v_mfma_f32_32x32x16_bf16 v[16:31], v[32:35], v[36:39], v[16:31]
	ds_read_b128 v[32:35], v206 offset:17408
	ds_read_b128 v[36:39], v207
	ds_read_b128 v[214:217], v206 offset:17440
	ds_read_b128 v[218:221], v207 offset:32
	s_waitcnt lgkmcnt(4)
	v_mfma_f32_32x32x16_bf16 v[16:31], v[40:43], v[44:47], v[16:31]
	s_waitcnt lgkmcnt(2)
	v_mfma_f32_32x32x16_bf16 v[32:47], v[32:35], v[36:39], 0
	s_waitcnt lgkmcnt(0)
	v_mfma_f32_32x32x16_bf16 v[32:47], v[214:217], v[218:221], v[32:47]
	ds_read_b128 v[214:217], v206 offset:17472
	ds_read_b128 v[218:221], v207 offset:64
	ds_read_b128 v[222:225], v206 offset:17504
	ds_read_b128 v[226:229], v207 offset:96
	s_waitcnt lgkmcnt(2)
	v_mfma_f32_32x32x16_bf16 v[32:47], v[214:217], v[218:221], v[32:47]
	s_waitcnt lgkmcnt(0)
	v_mfma_f32_32x32x16_bf16 v[32:47], v[222:225], v[226:229], v[32:47]
	ds_read_b128 v[214:217], v206 offset:17536
	ds_read_b128 v[218:221], v207 offset:128
	ds_read_b128 v[222:225], v206 offset:17568
	ds_read_b128 v[226:229], v207 offset:160
	s_waitcnt lgkmcnt(2)
	v_mfma_f32_32x32x16_bf16 v[32:47], v[214:217], v[218:221], v[32:47]
	s_waitcnt lgkmcnt(0)
	v_mfma_f32_32x32x16_bf16 v[32:47], v[222:225], v[226:229], v[32:47]
	ds_read_b128 v[214:217], v206 offset:17600
	ds_read_b128 v[218:221], v207 offset:192
	ds_read_b128 v[222:225], v206 offset:17632
	ds_read_b128 v[226:229], v207 offset:224
	s_waitcnt lgkmcnt(2)
	v_mfma_f32_32x32x16_bf16 v[32:47], v[214:217], v[218:221], v[32:47]
	v_lshl_add_u64 v[214:215], s[84:85], 0, v[152:153]
	v_lshlrev_b64 v[214:215], 11, v[214:215]
	v_lshl_add_u64 v[214:215], v[150:151], 0, v[214:215]
	s_waitcnt lgkmcnt(0)
	v_mfma_f32_32x32x16_bf16 v[32:47], v[222:225], v[226:229], v[32:47]
	s_nop 11
	v_add_f32_e32 v16, v16, v32
	v_cvt_pk_bf16_f32 v16, v16, s0
	global_store_short v[214:215], v16, off
	v_add_f32_e32 v16, v17, v33
	v_cvt_pk_bf16_f32 v32, v16, s0
	v_lshl_add_u64 v[16:17], s[84:85], 0, v[154:155]
	v_lshlrev_b64 v[16:17], 11, v[16:17]
	v_lshl_add_u64 v[16:17], v[150:151], 0, v[16:17]
	global_store_short v[16:17], v32, off
	v_add_f32_e32 v16, v18, v34
	v_cvt_pk_bf16_f32 v18, v16, s0
	v_lshl_add_u64 v[16:17], s[84:85], 0, v[156:157]
	v_lshlrev_b64 v[16:17], 11, v[16:17]
	v_lshl_add_u64 v[16:17], v[150:151], 0, v[16:17]
	global_store_short v[16:17], v18, off
	v_add_f32_e32 v16, v19, v35
	v_cvt_pk_bf16_f32 v18, v16, s0
	v_lshl_add_u64 v[16:17], s[84:85], 0, v[158:159]
	v_lshlrev_b64 v[16:17], 11, v[16:17]
	v_lshl_add_u64 v[16:17], v[150:151], 0, v[16:17]
	global_store_short v[16:17], v18, off
	v_add_f32_e32 v16, v20, v36
	v_cvt_pk_bf16_f32 v18, v16, s0
	v_lshl_add_u64 v[16:17], s[84:85], 0, v[160:161]
	v_lshlrev_b64 v[16:17], 11, v[16:17]
	v_lshl_add_u64 v[16:17], v[150:151], 0, v[16:17]
	global_store_short v[16:17], v18, off
	v_add_f32_e32 v16, v21, v37
	v_cvt_pk_bf16_f32 v18, v16, s0
	v_lshl_add_u64 v[16:17], s[84:85], 0, v[162:163]
	v_lshlrev_b64 v[16:17], 11, v[16:17]
	v_lshl_add_u64 v[16:17], v[150:151], 0, v[16:17]
	global_store_short v[16:17], v18, off
	v_add_f32_e32 v16, v22, v38
	v_cvt_pk_bf16_f32 v18, v16, s0
	v_lshl_add_u64 v[16:17], s[84:85], 0, v[164:165]
	v_lshlrev_b64 v[16:17], 11, v[16:17]
	v_lshl_add_u64 v[16:17], v[150:151], 0, v[16:17]
	global_store_short v[16:17], v18, off
	v_add_f32_e32 v16, v23, v39
	v_cvt_pk_bf16_f32 v18, v16, s0
	v_lshl_add_u64 v[16:17], s[84:85], 0, v[166:167]
	v_lshlrev_b64 v[16:17], 11, v[16:17]
	v_lshl_add_u64 v[16:17], v[150:151], 0, v[16:17]
	global_store_short v[16:17], v18, off
	v_add_f32_e32 v16, v24, v40
	v_cvt_pk_bf16_f32 v18, v16, s0
	v_lshl_add_u64 v[16:17], s[84:85], 0, v[168:169]
	v_lshlrev_b64 v[16:17], 11, v[16:17]
	v_lshl_add_u64 v[16:17], v[150:151], 0, v[16:17]
	global_store_short v[16:17], v18, off
	v_add_f32_e32 v16, v25, v41
	v_cvt_pk_bf16_f32 v18, v16, s0
	v_lshl_add_u64 v[16:17], s[84:85], 0, v[170:171]
	v_lshlrev_b64 v[16:17], 11, v[16:17]
	v_lshl_add_u64 v[16:17], v[150:151], 0, v[16:17]
	global_store_short v[16:17], v18, off
	v_add_f32_e32 v16, v26, v42
	v_cvt_pk_bf16_f32 v18, v16, s0
	v_lshl_add_u64 v[16:17], s[84:85], 0, v[172:173]
	v_lshlrev_b64 v[16:17], 11, v[16:17]
	v_lshl_add_u64 v[16:17], v[150:151], 0, v[16:17]
	global_store_short v[16:17], v18, off
	v_add_f32_e32 v16, v27, v43
	v_cvt_pk_bf16_f32 v18, v16, s0
	v_lshl_add_u64 v[16:17], s[84:85], 0, v[174:175]
	v_lshlrev_b64 v[16:17], 11, v[16:17]
	v_lshl_add_u64 v[16:17], v[150:151], 0, v[16:17]
	global_store_short v[16:17], v18, off
	v_add_f32_e32 v16, v28, v44
	v_cvt_pk_bf16_f32 v18, v16, s0
	v_lshl_add_u64 v[16:17], s[84:85], 0, v[176:177]
	v_lshlrev_b64 v[16:17], 11, v[16:17]
	v_lshl_add_u64 v[16:17], v[150:151], 0, v[16:17]
	global_store_short v[16:17], v18, off
	v_add_f32_e32 v16, v29, v45
	v_cvt_pk_bf16_f32 v18, v16, s0
	v_lshl_add_u64 v[16:17], s[84:85], 0, v[178:179]
	v_lshlrev_b64 v[16:17], 11, v[16:17]
	v_lshl_add_u64 v[16:17], v[150:151], 0, v[16:17]
	global_store_short v[16:17], v18, off
	v_add_f32_e32 v16, v30, v46
	v_cvt_pk_bf16_f32 v18, v16, s0
	v_lshl_add_u64 v[16:17], s[84:85], 0, v[180:181]
	v_lshlrev_b64 v[16:17], 11, v[16:17]
	v_lshl_add_u64 v[16:17], v[150:151], 0, v[16:17]
	global_store_short v[16:17], v18, off
	v_add_f32_e32 v16, v31, v47
	v_cvt_pk_bf16_f32 v18, v16, s0
	v_lshl_add_u64 v[16:17], s[84:85], 0, v[182:183]
	v_lshlrev_b64 v[16:17], 11, v[16:17]
	v_lshl_add_u64 v[16:17], v[150:151], 0, v[16:17]
	global_store_short v[16:17], v18, off

.LBB0_889:
	s_or_b64 exec, exec, s[52:53]
	s_sub_i32 s10, s79, 64
	s_add_i32 s81, s80, 64
	s_and_b64 s[52:53], s[48:49], exec
	s_cselect_b32 s10, s10, s81
	v_lshl_add_u64 v[16:17], v[148:149], 0, s[10:11]
	v_lshlrev_b64 v[16:17], 11, v[16:17]
	v_lshl_add_u64 v[16:17], v[146:147], 0, v[16:17]
	global_load_dwordx4 v[136:139], v[16:17], off
	s_waitcnt vmcnt(23)
	ds_write_b128 v202, v[112:115] offset:17408
	s_waitcnt vmcnt(22)
	ds_write_b128 v202, v[116:119] offset:17424
	s_waitcnt vmcnt(21)
	ds_write_b128 v203, v[124:127] offset:34816
	s_waitcnt vmcnt(20)
	ds_write_b128 v203, v[128:131] offset:34832
	s_waitcnt vmcnt(19)
	ds_write_b128 v204, v[132:135] offset:53248
	s_waitcnt vmcnt(18)
	s_branch .Lsw5_join

.Lsw5_join:
	ds_write_b16 v144, v140 offset:62464
	ds_write_b16_d16_hi v144, v140 offset:62608
	ds_write_b16 v144, v141 offset:62752
	ds_write_b16_d16_hi v144, v141 offset:62896
	ds_write_b16 v144, v142 offset:63040
	ds_write_b16_d16_hi v144, v142 offset:63184
	ds_write_b16 v144, v143 offset:63328
	ds_write_b16_d16_hi v144, v143 offset:63472
	s_and_saveexec_b64 s[52:53], s[0:1]
	ds_write_b32 v205, v200
	s_or_b64 exec, exec, s[52:53]
	s_waitcnt lgkmcnt(0)
	s_barrier
	s_and_saveexec_b64 s[52:53], s[4:5]
	s_cbranch_execz .LBB0_894
	ds_read_b128 v[16:19], v209 offset:53248
	ds_read_b128 v[20:23], v210 offset:62464
	ds_read_b128 v[32:35], v209 offset:53280
	ds_read_b128 v[36:39], v210 offset:62496
	s_add_i32 s10, s79, 0xffffff00
	s_add_i32 s81, s80, 0x100
	s_waitcnt lgkmcnt(2)
	v_mfma_f32_32x32x16_bf16 v[16:31], v[16:19], v[20:23], 0
	s_and_b64 s[84:85], s[48:49], exec
	s_cselect_b32 s10, s10, s81
	s_add_u32 s84, s46, s10
	s_addc_u32 s85, 0, s47
	s_waitcnt lgkmcnt(0)
	v_mfma_f32_32x32x16_bf16 v[16:31], v[32:35], v[36:39], v[16:31]
	ds_read_b128 v[32:35], v209 offset:53312
	ds_read_b128 v[36:39], v210 offset:62528
	ds_read_b128 v[40:43], v209 offset:53344
	ds_read_b128 v[44:47], v210 offset:62560
	s_waitcnt lgkmcnt(2)
	v_mfma_f32_32x32x16_bf16 v[16:31], v[32:35], v[36:39], v[16:31]
	ds_read_b128 v[32:35], v206 offset:17408
	ds_read_b128 v[36:39], v207
	ds_read_b128 v[214:217], v206 offset:17440
	ds_read_b128 v[218:221], v207 offset:32
	s_waitcnt lgkmcnt(4)
	v_mfma_f32_32x32x16_bf16 v[16:31], v[40:43], v[44:47], v[16:31]
	s_waitcnt lgkmcnt(2)
	v_mfma_f32_32x32x16_bf16 v[32:47], v[32:35], v[36:39], 0
	s_waitcnt lgkmcnt(0)
	v_mfma_f32_32x32x16_bf16 v[32:47], v[214:217], v[218:221], v[32:47]
	ds_read_b128 v[214:217], v206 offset:17472
	ds_read_b128 v[218:221], v207 offset:64
	ds_read_b128 v[222:225], v206 offset:17504
	ds_read_b128 v[226:229], v207 offset:96
	s_waitcnt lgkmcnt(2)
	v_mfma_f32_32x32x16_bf16 v[32:47], v[214:217], v[218:221], v[32:47]
	s_waitcnt lgkmcnt(0)
	v_mfma_f32_32x32x16_bf16 v[32:47], v[222:225], v[226:229], v[32:47]
	ds_read_b128 v[214:217], v206 offset:17536
	ds_read_b128 v[218:221], v207 offset:128
	ds_read_b128 v[222:225], v206 offset:17568
	ds_read_b128 v[226:229], v207 offset:160
	s_waitcnt lgkmcnt(2)
	v_mfma_f32_32x32x16_bf16 v[32:47], v[214:217], v[218:221], v[32:47]
	s_waitcnt lgkmcnt(0)
	v_mfma_f32_32x32x16_bf16 v[32:47], v[222:225], v[226:229], v[32:47]
	ds_read_b128 v[214:217], v206 offset:17600
	ds_read_b128 v[218:221], v207 offset:192
	ds_read_b128 v[222:225], v206 offset:17632
	ds_read_b128 v[226:229], v207 offset:224
	s_waitcnt lgkmcnt(2)
	v_mfma_f32_32x32x16_bf16 v[32:47], v[214:217], v[218:221], v[32:47]
	v_lshl_add_u64 v[214:215], s[84:85], 0, v[152:153]
	v_lshlrev_b64 v[214:215], 11, v[214:215]
	v_lshl_add_u64 v[214:215], v[150:151], 0, v[214:215]
	s_waitcnt lgkmcnt(0)
	v_mfma_f32_32x32x16_bf16 v[32:47], v[222:225], v[226:229], v[32:47]
	s_nop 11
	v_add_f32_e32 v16, v16, v32
	v_cvt_pk_bf16_f32 v16, v16, s0
	global_store_short v[214:215], v16, off
	v_add_f32_e32 v16, v17, v33
	v_cvt_pk_bf16_f32 v32, v16, s0
	v_lshl_add_u64 v[16:17], s[84:85], 0, v[154:155]
	v_lshlrev_b64 v[16:17], 11, v[16:17]
	v_lshl_add_u64 v[16:17], v[150:151], 0, v[16:17]
	global_store_short v[16:17], v32, off
	v_add_f32_e32 v16, v18, v34
	v_cvt_pk_bf16_f32 v18, v16, s0
	v_lshl_add_u64 v[16:17], s[84:85], 0, v[156:157]
	v_lshlrev_b64 v[16:17], 11, v[16:17]
	v_lshl_add_u64 v[16:17], v[150:151], 0, v[16:17]
	global_store_short v[16:17], v18, off
	v_add_f32_e32 v16, v19, v35
	v_cvt_pk_bf16_f32 v18, v16, s0
	v_lshl_add_u64 v[16:17], s[84:85], 0, v[158:159]
	v_lshlrev_b64 v[16:17], 11, v[16:17]
	v_lshl_add_u64 v[16:17], v[150:151], 0, v[16:17]
	global_store_short v[16:17], v18, off
	v_add_f32_e32 v16, v20, v36
	v_cvt_pk_bf16_f32 v18, v16, s0
	v_lshl_add_u64 v[16:17], s[84:85], 0, v[160:161]
	v_lshlrev_b64 v[16:17], 11, v[16:17]
	v_lshl_add_u64 v[16:17], v[150:151], 0, v[16:17]
	global_store_short v[16:17], v18, off
	v_add_f32_e32 v16, v21, v37
	v_cvt_pk_bf16_f32 v18, v16, s0
	v_lshl_add_u64 v[16:17], s[84:85], 0, v[162:163]
	v_lshlrev_b64 v[16:17], 11, v[16:17]
	v_lshl_add_u64 v[16:17], v[150:151], 0, v[16:17]
	global_store_short v[16:17], v18, off
	v_add_f32_e32 v16, v22, v38
	v_cvt_pk_bf16_f32 v18, v16, s0
	v_lshl_add_u64 v[16:17], s[84:85], 0, v[164:165]
	v_lshlrev_b64 v[16:17], 11, v[16:17]
	v_lshl_add_u64 v[16:17], v[150:151], 0, v[16:17]
	global_store_short v[16:17], v18, off
	v_add_f32_e32 v16, v23, v39
	v_cvt_pk_bf16_f32 v18, v16, s0
	v_lshl_add_u64 v[16:17], s[84:85], 0, v[166:167]
	v_lshlrev_b64 v[16:17], 11, v[16:17]
	v_lshl_add_u64 v[16:17], v[150:151], 0, v[16:17]
	global_store_short v[16:17], v18, off
	v_add_f32_e32 v16, v24, v40
	v_cvt_pk_bf16_f32 v18, v16, s0
	v_lshl_add_u64 v[16:17], s[84:85], 0, v[168:169]
	v_lshlrev_b64 v[16:17], 11, v[16:17]
	v_lshl_add_u64 v[16:17], v[150:151], 0, v[16:17]
	global_store_short v[16:17], v18, off
	v_add_f32_e32 v16, v25, v41
	v_cvt_pk_bf16_f32 v18, v16, s0
	v_lshl_add_u64 v[16:17], s[84:85], 0, v[170:171]
	v_lshlrev_b64 v[16:17], 11, v[16:17]
	v_lshl_add_u64 v[16:17], v[150:151], 0, v[16:17]
	global_store_short v[16:17], v18, off
	v_add_f32_e32 v16, v26, v42
	v_cvt_pk_bf16_f32 v18, v16, s0
	v_lshl_add_u64 v[16:17], s[84:85], 0, v[172:173]
	v_lshlrev_b64 v[16:17], 11, v[16:17]
	v_lshl_add_u64 v[16:17], v[150:151], 0, v[16:17]
	global_store_short v[16:17], v18, off
	v_add_f32_e32 v16, v27, v43
	v_cvt_pk_bf16_f32 v18, v16, s0
	v_lshl_add_u64 v[16:17], s[84:85], 0, v[174:175]
	v_lshlrev_b64 v[16:17], 11, v[16:17]
	v_lshl_add_u64 v[16:17], v[150:151], 0, v[16:17]
	global_store_short v[16:17], v18, off
	v_add_f32_e32 v16, v28, v44
	v_cvt_pk_bf16_f32 v18, v16, s0
	v_lshl_add_u64 v[16:17], s[84:85], 0, v[176:177]
	v_lshlrev_b64 v[16:17], 11, v[16:17]
	v_lshl_add_u64 v[16:17], v[150:151], 0, v[16:17]
	global_store_short v[16:17], v18, off
	v_add_f32_e32 v16, v29, v45
	v_cvt_pk_bf16_f32 v18, v16, s0
	v_lshl_add_u64 v[16:17], s[84:85], 0, v[178:179]
	v_lshlrev_b64 v[16:17], 11, v[16:17]
	v_lshl_add_u64 v[16:17], v[150:151], 0, v[16:17]
	global_store_short v[16:17], v18, off
	v_add_f32_e32 v16, v30, v46
	v_cvt_pk_bf16_f32 v18, v16, s0
	v_lshl_add_u64 v[16:17], s[84:85], 0, v[180:181]
	v_lshlrev_b64 v[16:17], 11, v[16:17]
	v_lshl_add_u64 v[16:17], v[150:151], 0, v[16:17]
	global_store_short v[16:17], v18, off
	v_add_f32_e32 v16, v31, v47
	v_cvt_pk_bf16_f32 v18, v16, s0
	v_lshl_add_u64 v[16:17], s[84:85], 0, v[182:183]
	v_lshlrev_b64 v[16:17], 11, v[16:17]
	v_lshl_add_u64 v[16:17], v[150:151], 0, v[16:17]
	global_store_short v[16:17], v18, off
